# plus small_gates K-loop de-serialized by hand (24-48 loads in flight instead of 32 load-wait-MFMA round trips), same MFMA order
# speedup vs baseline: 1.0168x; 1.0030x over previous
.LBB0_149:
	global_load_dwordx4 v[24:27], v[12:13], off offset:0
	global_load_dwordx4 v[28:31], v[16:17], off offset:0
	global_load_dwordx4 v[32:35], v[14:15], off offset:0
	global_load_dwordx4 v[36:39], v[12:13], off offset:64
	global_load_dwordx4 v[40:43], v[16:17], off offset:64
	global_load_dwordx4 v[44:47], v[14:15], off offset:64
	global_load_dwordx4 v[48:51], v[12:13], off offset:128
	global_load_dwordx4 v[52:55], v[16:17], off offset:128
	global_load_dwordx4 v[56:59], v[14:15], off offset:128
	global_load_dwordx4 v[60:63], v[12:13], off offset:192
	global_load_dwordx4 v[64:67], v[16:17], off offset:192
	global_load_dwordx4 v[68:71], v[14:15], off offset:192
	global_load_dwordx4 v[72:75], v[12:13], off offset:256
	global_load_dwordx4 v[76:79], v[16:17], off offset:256
	global_load_dwordx4 v[80:83], v[14:15], off offset:256
	global_load_dwordx4 v[84:87], v[12:13], off offset:320
	global_load_dwordx4 v[88:91], v[16:17], off offset:320
	global_load_dwordx4 v[92:95], v[14:15], off offset:320
	global_load_dwordx4 v[96:99], v[12:13], off offset:384
	global_load_dwordx4 v[100:103], v[16:17], off offset:384
	global_load_dwordx4 v[104:107], v[14:15], off offset:384
	global_load_dwordx4 v[108:111], v[12:13], off offset:448
	global_load_dwordx4 v[112:115], v[16:17], off offset:448
	global_load_dwordx4 v[116:119], v[14:15], off offset:448
	global_load_dwordx4 v[120:123], v[12:13], off offset:512
	global_load_dwordx4 v[124:127], v[16:17], off offset:512
	global_load_dwordx4 v[128:131], v[14:15], off offset:512
	global_load_dwordx4 v[132:135], v[12:13], off offset:576
	global_load_dwordx4 v[136:139], v[16:17], off offset:576
	global_load_dwordx4 v[140:143], v[14:15], off offset:576
	global_load_dwordx4 v[148:151], v[12:13], off offset:640
	global_load_dwordx4 v[152:155], v[16:17], off offset:640
	global_load_dwordx4 v[156:159], v[14:15], off offset:640
	global_load_dwordx4 v[160:163], v[12:13], off offset:704
	global_load_dwordx4 v[164:167], v[16:17], off offset:704
	global_load_dwordx4 v[184:187], v[14:15], off offset:704
	global_load_dwordx4 v[188:191], v[12:13], off offset:768
	global_load_dwordx4 v[192:195], v[16:17], off offset:768
	global_load_dwordx4 v[196:199], v[14:15], off offset:768
	global_load_dwordx4 v[200:203], v[12:13], off offset:832
	global_load_dwordx4 v[204:207], v[16:17], off offset:832
	global_load_dwordx4 v[208:211], v[14:15], off offset:832
	global_load_dwordx4 v[212:215], v[12:13], off offset:896
	global_load_dwordx4 v[216:219], v[16:17], off offset:896
	global_load_dwordx4 v[224:227], v[14:15], off offset:896
	global_load_dwordx4 v[228:231], v[12:13], off offset:960
	global_load_dwordx4 v[232:235], v[16:17], off offset:960
	global_load_dwordx4 v[236:239], v[14:15], off offset:960
	s_waitcnt vmcnt(24)
	v_mfma_f32_16x16x32_bf16 v[2:5], v[24:27], v[32:35], v[2:5]
	v_mfma_f32_16x16x32_bf16 v[6:9], v[28:31], v[32:35], v[6:9]
	v_mfma_f32_16x16x32_bf16 v[2:5], v[36:39], v[44:47], v[2:5]
	v_mfma_f32_16x16x32_bf16 v[6:9], v[40:43], v[44:47], v[6:9]
	v_mfma_f32_16x16x32_bf16 v[2:5], v[48:51], v[56:59], v[2:5]
	v_mfma_f32_16x16x32_bf16 v[6:9], v[52:55], v[56:59], v[6:9]
	v_mfma_f32_16x16x32_bf16 v[2:5], v[60:63], v[68:71], v[2:5]
	v_mfma_f32_16x16x32_bf16 v[6:9], v[64:67], v[68:71], v[6:9]
	v_mfma_f32_16x16x32_bf16 v[2:5], v[72:75], v[80:83], v[2:5]
	v_mfma_f32_16x16x32_bf16 v[6:9], v[76:79], v[80:83], v[6:9]
	v_mfma_f32_16x16x32_bf16 v[2:5], v[84:87], v[92:95], v[2:5]
	v_mfma_f32_16x16x32_bf16 v[6:9], v[88:91], v[92:95], v[6:9]
	v_mfma_f32_16x16x32_bf16 v[2:5], v[96:99], v[104:107], v[2:5]
	v_mfma_f32_16x16x32_bf16 v[6:9], v[100:103], v[104:107], v[6:9]
	v_mfma_f32_16x16x32_bf16 v[2:5], v[108:111], v[116:119], v[2:5]
	v_mfma_f32_16x16x32_bf16 v[6:9], v[112:115], v[116:119], v[6:9]
	global_load_dwordx4 v[24:27], v[12:13], off offset:1024
	global_load_dwordx4 v[28:31], v[16:17], off offset:1024
	global_load_dwordx4 v[32:35], v[14:15], off offset:1024
	global_load_dwordx4 v[36:39], v[12:13], off offset:1088
	global_load_dwordx4 v[40:43], v[16:17], off offset:1088
	global_load_dwordx4 v[44:47], v[14:15], off offset:1088
	global_load_dwordx4 v[48:51], v[12:13], off offset:1152
	global_load_dwordx4 v[52:55], v[16:17], off offset:1152
	global_load_dwordx4 v[56:59], v[14:15], off offset:1152
	global_load_dwordx4 v[60:63], v[12:13], off offset:1216
	global_load_dwordx4 v[64:67], v[16:17], off offset:1216
	global_load_dwordx4 v[68:71], v[14:15], off offset:1216
	global_load_dwordx4 v[72:75], v[12:13], off offset:1280
	global_load_dwordx4 v[76:79], v[16:17], off offset:1280
	global_load_dwordx4 v[80:83], v[14:15], off offset:1280
	global_load_dwordx4 v[84:87], v[12:13], off offset:1344
	global_load_dwordx4 v[88:91], v[16:17], off offset:1344
	global_load_dwordx4 v[92:95], v[14:15], off offset:1344
	global_load_dwordx4 v[96:99], v[12:13], off offset:1408
	global_load_dwordx4 v[100:103], v[16:17], off offset:1408
	global_load_dwordx4 v[104:107], v[14:15], off offset:1408
	global_load_dwordx4 v[108:111], v[12:13], off offset:1472
	global_load_dwordx4 v[112:115], v[16:17], off offset:1472
	global_load_dwordx4 v[116:119], v[14:15], off offset:1472
	s_waitcnt vmcnt(24)
	v_mfma_f32_16x16x32_bf16 v[2:5], v[120:123], v[128:131], v[2:5]
	v_mfma_f32_16x16x32_bf16 v[6:9], v[124:127], v[128:131], v[6:9]
	v_mfma_f32_16x16x32_bf16 v[2:5], v[132:135], v[140:143], v[2:5]
	v_mfma_f32_16x16x32_bf16 v[6:9], v[136:139], v[140:143], v[6:9]
	v_mfma_f32_16x16x32_bf16 v[2:5], v[148:151], v[156:159], v[2:5]
	v_mfma_f32_16x16x32_bf16 v[6:9], v[152:155], v[156:159], v[6:9]
	v_mfma_f32_16x16x32_bf16 v[2:5], v[160:163], v[184:187], v[2:5]
	v_mfma_f32_16x16x32_bf16 v[6:9], v[164:167], v[184:187], v[6:9]
	v_mfma_f32_16x16x32_bf16 v[2:5], v[188:191], v[196:199], v[2:5]
	v_mfma_f32_16x16x32_bf16 v[6:9], v[192:195], v[196:199], v[6:9]
	v_mfma_f32_16x16x32_bf16 v[2:5], v[200:203], v[208:211], v[2:5]
	v_mfma_f32_16x16x32_bf16 v[6:9], v[204:207], v[208:211], v[6:9]
	v_mfma_f32_16x16x32_bf16 v[2:5], v[212:215], v[224:227], v[2:5]
	v_mfma_f32_16x16x32_bf16 v[6:9], v[216:219], v[224:227], v[6:9]
	v_mfma_f32_16x16x32_bf16 v[2:5], v[228:231], v[236:239], v[2:5]
	v_mfma_f32_16x16x32_bf16 v[6:9], v[232:235], v[236:239], v[6:9]
	global_load_dwordx4 v[120:123], v[12:13], off offset:1536
	global_load_dwordx4 v[124:127], v[16:17], off offset:1536
	global_load_dwordx4 v[128:131], v[14:15], off offset:1536
	global_load_dwordx4 v[132:135], v[12:13], off offset:1600
	global_load_dwordx4 v[136:139], v[16:17], off offset:1600
	global_load_dwordx4 v[140:143], v[14:15], off offset:1600
	global_load_dwordx4 v[148:151], v[12:13], off offset:1664
	global_load_dwordx4 v[152:155], v[16:17], off offset:1664
	global_load_dwordx4 v[156:159], v[14:15], off offset:1664
	global_load_dwordx4 v[160:163], v[12:13], off offset:1728
	global_load_dwordx4 v[164:167], v[16:17], off offset:1728
	global_load_dwordx4 v[184:187], v[14:15], off offset:1728
	global_load_dwordx4 v[188:191], v[12:13], off offset:1792
	global_load_dwordx4 v[192:195], v[16:17], off offset:1792
	global_load_dwordx4 v[196:199], v[14:15], off offset:1792
	global_load_dwordx4 v[200:203], v[12:13], off offset:1856
	global_load_dwordx4 v[204:207], v[16:17], off offset:1856
	global_load_dwordx4 v[208:211], v[14:15], off offset:1856
	global_load_dwordx4 v[212:215], v[12:13], off offset:1920
	global_load_dwordx4 v[216:219], v[16:17], off offset:1920
	global_load_dwordx4 v[224:227], v[14:15], off offset:1920
	global_load_dwordx4 v[228:231], v[12:13], off offset:1984
	global_load_dwordx4 v[232:235], v[16:17], off offset:1984
	global_load_dwordx4 v[236:239], v[14:15], off offset:1984
	s_waitcnt vmcnt(24)
	v_mfma_f32_16x16x32_bf16 v[2:5], v[24:27], v[32:35], v[2:5]
	v_mfma_f32_16x16x32_bf16 v[6:9], v[28:31], v[32:35], v[6:9]
	v_mfma_f32_16x16x32_bf16 v[2:5], v[36:39], v[44:47], v[2:5]
	v_mfma_f32_16x16x32_bf16 v[6:9], v[40:43], v[44:47], v[6:9]
	v_mfma_f32_16x16x32_bf16 v[2:5], v[48:51], v[56:59], v[2:5]
	v_mfma_f32_16x16x32_bf16 v[6:9], v[52:55], v[56:59], v[6:9]
	v_mfma_f32_16x16x32_bf16 v[2:5], v[60:63], v[68:71], v[2:5]
	v_mfma_f32_16x16x32_bf16 v[6:9], v[64:67], v[68:71], v[6:9]
	v_mfma_f32_16x16x32_bf16 v[2:5], v[72:75], v[80:83], v[2:5]
	v_mfma_f32_16x16x32_bf16 v[6:9], v[76:79], v[80:83], v[6:9]
	v_mfma_f32_16x16x32_bf16 v[2:5], v[84:87], v[92:95], v[2:5]
	v_mfma_f32_16x16x32_bf16 v[6:9], v[88:91], v[92:95], v[6:9]
	v_mfma_f32_16x16x32_bf16 v[2:5], v[96:99], v[104:107], v[2:5]
	v_mfma_f32_16x16x32_bf16 v[6:9], v[100:103], v[104:107], v[6:9]
	v_mfma_f32_16x16x32_bf16 v[2:5], v[108:111], v[116:119], v[2:5]
	v_mfma_f32_16x16x32_bf16 v[6:9], v[112:115], v[116:119], v[6:9]
	s_waitcnt vmcnt(0)
	v_mfma_f32_16x16x32_bf16 v[2:5], v[120:123], v[128:131], v[2:5]
	v_mfma_f32_16x16x32_bf16 v[6:9], v[124:127], v[128:131], v[6:9]
	v_mfma_f32_16x16x32_bf16 v[2:5], v[132:135], v[140:143], v[2:5]
	v_mfma_f32_16x16x32_bf16 v[6:9], v[136:139], v[140:143], v[6:9]
	v_mfma_f32_16x16x32_bf16 v[2:5], v[148:151], v[156:159], v[2:5]
	v_mfma_f32_16x16x32_bf16 v[6:9], v[152:155], v[156:159], v[6:9]
	v_mfma_f32_16x16x32_bf16 v[2:5], v[160:163], v[184:187], v[2:5]
	v_mfma_f32_16x16x32_bf16 v[6:9], v[164:167], v[184:187], v[6:9]
	v_mfma_f32_16x16x32_bf16 v[2:5], v[188:191], v[196:199], v[2:5]
	v_mfma_f32_16x16x32_bf16 v[6:9], v[192:195], v[196:199], v[6:9]
	v_mfma_f32_16x16x32_bf16 v[2:5], v[200:203], v[208:211], v[2:5]
	v_mfma_f32_16x16x32_bf16 v[6:9], v[204:207], v[208:211], v[6:9]
	v_mfma_f32_16x16x32_bf16 v[2:5], v[212:215], v[224:227], v[2:5]
	v_mfma_f32_16x16x32_bf16 v[6:9], v[216:219], v[224:227], v[6:9]
	v_mfma_f32_16x16x32_bf16 v[2:5], v[228:231], v[236:239], v[2:5]
	v_mfma_f32_16x16x32_bf16 v[6:9], v[232:235], v[236:239], v[6:9]
	v_lshl_add_u64 v[12:13], v[10:11], 3, s[34:35]
	flat_load_dwordx2 v[12:13], v[12:13]
	v_mov_b64_e32 v[14:15], s[26:27]
	s_waitcnt vmcnt(0) lgkmcnt(0)
	v_ffbh_u32_e32 v0, v13
	v_min_u32_e32 v0, 32, v0
	v_lshlrev_b64 v[12:13], v0, v[12:13]
	v_min_u32_e32 v11, 1, v12
	v_or_b32_e32 v11, v13, v11
	v_cvt_f32_u32_e32 v11, v11
	v_sub_u32_e32 v0, 32, v0
	v_ldexp_f32 v0, v11, v0
	v_mul_f32_e32 v0, 0x35800000, v0
	v_fmamk_f32 v0, v0, 0x3a800000, v173
	v_cmp_gt_f32_e32 vcc, s96, v0
	v_mul_f32_e32 v11, 0x4b800000, v0
	s_nop 0
	v_cndmask_b32_e32 v0, v0, v11, vcc
	v_rsq_f32_e32 v0, v0
	s_nop 0
	v_mul_f32_e32 v11, 0x45800000, v0
	v_cndmask_b32_e32 v12, v0, v11, vcc
	v_mad_i64_i32 v[10:11], s[2:3], v10, s18, v[14:15]
	v_lshlrev_b32_e32 v0, 3, v23
	v_lshl_add_u64 v[10:11], v[10:11], 0, v[0:1]
	v_pk_mul_f32 v[2:3], v[2:3], v[12:13] op_sel_hi:[1,0]
	v_pk_mul_f32 v[4:5], v[4:5], v[12:13] op_sel_hi:[1,0]
	v_cvt_pk_bf16_f32 v2, v2, v3
	v_cvt_pk_bf16_f32 v3, v4, v5
	v_add_co_u32_e32 v4, vcc, 0x1000, v10
	s_nop 1
	v_addc_co_u32_e32 v5, vcc, 0, v11, vcc
	v_cmp_gt_u32_e32 vcc, 32, v22
	flat_store_dwordx2 v[4:5], v[2:3] offset:3072
	s_and_saveexec_b64 s[2:3], vcc
	s_cbranch_execz .LBB0_147
	v_mov_b32_e32 v13, v12
	s_mov_b64 s[4:5], 0x1c00
	v_pk_mul_f32 v[4:5], v[6:7], v[12:13]
	v_pk_mul_f32 v[6:7], v[8:9], v[12:13]
	v_lshl_add_u64 v[2:3], v[10:11], 0, s[4:5]
	v_cvt_pk_bf16_f32 v4, v4, v5
	v_cvt_pk_bf16_f32 v5, v6, v7
	flat_store_dwordx2 v[2:3], v[4:5] offset:32
	s_branch .LBB0_147
